# MO8+TRIM + first-iteration vmcnt over-wait relaxation (W1/W2 = vmcnt(8+stores) when K counter == -2 and unit != first)
# baseline (speedup 1.0000x reference)
.LBB0_139:
	s_add_u32 s22, s18, 0xfff00080
	s_addc_u32 s23, s19, -1
	s_add_i32 s49, 0, 0x10000
	s_cmp_eq_u32 s48, 60
	s_cselect_b32 s25, s9, s23
	s_cselect_b32 s24, s44, s22
	s_cselect_b32 s23, s7, s47
	s_cselect_b32 s22, s45, s46
	s_add_i32 s52, 0, 0x14000
	v_add_u32_e32 v156, s49, v145
	v_add_u32_e32 v172, s52, v145
	ds_read_b128 v[140:143], v156
	ds_read_b128 v[148:151], v156 offset:1024
	ds_read_b128 v[152:155], v156 offset:2048
	ds_read_b128 v[156:159], v156 offset:3072
	ds_read_b128 v[160:163], v172
	ds_read_b128 v[164:167], v172 offset:1024
	ds_read_b128 v[168:171], v172 offset:2048
	ds_read_b128 v[190:193], v172 offset:3072
	v_lshl_add_u64 v[172:173], s[18:19], 0, v[136:137]
	s_add_i32 m0, s31, 0xc000
	ds_read_b128 v[194:197], v147
	ds_read_b128 v[198:201], v147 offset:1024
	ds_read_b128 v[202:205], v147 offset:2048
	ds_read_b128 v[206:209], v147 offset:3072
	ds_read_b128 v[228:231], v147 offset:4096
	ds_read_b128 v[232:235], v147 offset:5120
	ds_read_b128 v[236:239], v147 offset:6144
	ds_read_b128 v[240:243], v147 offset:7168
	global_load_lds_dwordx4 v[172:173], off
	v_lshl_add_u64 v[172:173], s[18:19], 0, v[138:139]
	s_add_i32 m0, s31, 0xe000
	s_nop 0
	global_load_lds_dwordx4 v[172:173], off
	s_cmp_lg_u32 s48, 0xfffffffe
	s_cbranch_scc1 .Low_2_norm
	s_cmp_eq_u32 s41, 1
	s_cbranch_scc1 .Low_2_norm
	s_waitcnt vmcnt(24)
	s_branch .Low_2_done
.Low_2_norm:
	s_waitcnt vmcnt(8)
.Low_2_done:
	s_waitcnt lgkmcnt(0)
	s_setprio 1
	s_barrier
	v_mfma_f32_16x16x32_bf16 v[126:129], v[140:143], v[194:197], v[126:129]
	v_mfma_f32_16x16x32_bf16 v[126:129], v[148:151], v[198:201], v[126:129]
	v_mfma_f32_16x16x32_bf16 v[118:121], v[148:151], v[206:209], v[118:121]
	v_mfma_f32_16x16x32_bf16 v[118:121], v[140:143], v[202:205], v[118:121]
	v_mfma_f32_16x16x32_bf16 v[102:105], v[140:143], v[228:231], v[102:105]
	v_mfma_f32_16x16x32_bf16 v[102:105], v[148:151], v[232:235], v[102:105]
	v_mfma_f32_16x16x32_bf16 v[86:89], v[148:151], v[240:243], v[86:89]
	v_mfma_f32_16x16x32_bf16 v[86:89], v[140:143], v[236:239], v[86:89]
	v_mfma_f32_16x16x32_bf16 v[78:81], v[152:155], v[236:239], v[78:81]
	v_mfma_f32_16x16x32_bf16 v[78:81], v[156:159], v[240:243], v[78:81]
	v_mfma_f32_16x16x32_bf16 v[94:97], v[156:159], v[232:235], v[94:97]
	v_mfma_f32_16x16x32_bf16 v[94:97], v[152:155], v[228:231], v[94:97]
	v_mfma_f32_16x16x32_bf16 v[110:113], v[152:155], v[202:205], v[110:113]
	v_mfma_f32_16x16x32_bf16 v[110:113], v[156:159], v[206:209], v[110:113]
	v_mfma_f32_16x16x32_bf16 v[122:125], v[156:159], v[198:201], v[122:125]
	v_mfma_f32_16x16x32_bf16 v[122:125], v[152:155], v[194:197], v[122:125]
	v_mfma_f32_16x16x32_bf16 v[114:117], v[160:163], v[194:197], v[114:117]
	v_mfma_f32_16x16x32_bf16 v[114:117], v[164:167], v[198:201], v[114:117]
	v_mfma_f32_16x16x32_bf16 v[98:101], v[164:167], v[206:209], v[98:101]
	v_mfma_f32_16x16x32_bf16 v[98:101], v[160:163], v[202:205], v[98:101]
	v_mfma_f32_16x16x32_bf16 v[82:85], v[160:163], v[228:231], v[82:85]
	v_mfma_f32_16x16x32_bf16 v[82:85], v[164:167], v[232:235], v[82:85]
	v_mfma_f32_16x16x32_bf16 v[70:73], v[164:167], v[240:243], v[70:73]
	v_mfma_f32_16x16x32_bf16 v[70:73], v[160:163], v[236:239], v[70:73]
	v_mfma_f32_16x16x32_bf16 v[66:69], v[168:171], v[236:239], v[66:69]
	v_mfma_f32_16x16x32_bf16 v[66:69], v[190:193], v[240:243], v[66:69]
	v_mfma_f32_16x16x32_bf16 v[74:77], v[190:193], v[232:235], v[74:77]
	v_mfma_f32_16x16x32_bf16 v[74:77], v[168:171], v[228:231], v[74:77]
	v_mfma_f32_16x16x32_bf16 v[90:93], v[168:171], v[202:205], v[90:93]
	v_mfma_f32_16x16x32_bf16 v[90:93], v[190:193], v[206:209], v[90:93]
	v_mfma_f32_16x16x32_bf16 v[106:109], v[190:193], v[198:201], v[106:109]
	v_mfma_f32_16x16x32_bf16 v[106:109], v[168:171], v[194:197], v[106:109]
	s_barrier
	s_setprio 0
	s_add_i32 s49, s49, s26
	v_lshl_add_u64 v[172:173], s[22:23], 0, v[0:1]
	s_mov_b32 m0, s49
	ds_read_b128 v[194:197], v147 offset:16384
	ds_read_b128 v[198:201], v147 offset:17408
	ds_read_b128 v[202:205], v147 offset:18432
	ds_read_b128 v[206:209], v147 offset:19456
	ds_read_b128 v[228:231], v147 offset:20480
	ds_read_b128 v[232:235], v147 offset:21504
	ds_read_b128 v[236:239], v147 offset:22528
	ds_read_b128 v[240:243], v147 offset:23552
	global_load_lds_dwordx4 v[172:173], off
	s_add_i32 m0, s49, 0x2000
	s_add_u32 s50, s22, 0x100000
	v_lshl_add_u64 v[178:179], s[22:23], 0, v[130:131]
	s_addc_u32 s51, s23, 0
	s_add_i32 s49, s52, s26
	global_load_lds_dwordx4 v[178:179], off
	v_lshl_add_u64 v[180:181], s[50:51], 0, v[0:1]
	s_mov_b32 m0, s49
	v_lshl_add_u64 v[210:211], s[24:25], 0, v[132:133]
	global_load_lds_dwordx4 v[180:181], off
	v_lshl_add_u64 v[180:181], s[50:51], 0, v[130:131]
	s_add_i32 m0, s49, 0x2000
	s_nop 0
	global_load_lds_dwordx4 v[180:181], off
	v_lshl_add_u64 v[180:181], s[24:25], 0, v[134:135]
	s_mov_b32 m0, s31
	s_nop 0
	global_load_lds_dwordx4 v[180:181], off
	s_mov_b32 m0, s36
	s_nop 0
	global_load_lds_dwordx4 v[210:211], off
	s_cmp_lg_u32 s48, 0xfffffffe
	s_cbranch_scc1 .Low_1_norm
	s_cmp_eq_u32 s41, 1
	s_cbranch_scc1 .Low_1_norm
	s_waitcnt vmcnt(24)
	s_branch .Low_1_done

.Low_1_done:
	s_waitcnt lgkmcnt(0)
	s_setprio 1
	s_barrier
	v_mfma_f32_16x16x32_bf16 v[62:65], v[140:143], v[194:197], v[62:65]
	v_mfma_f32_16x16x32_bf16 v[62:65], v[148:151], v[198:201], v[62:65]
	v_mfma_f32_16x16x32_bf16 v[54:57], v[148:151], v[206:209], v[54:57]
	v_mfma_f32_16x16x32_bf16 v[54:57], v[140:143], v[202:205], v[54:57]
	v_mfma_f32_16x16x32_bf16 v[38:41], v[140:143], v[228:231], v[38:41]
	v_mfma_f32_16x16x32_bf16 v[38:41], v[148:151], v[232:235], v[38:41]
	v_mfma_f32_16x16x32_bf16 v[22:25], v[148:151], v[240:243], v[22:25]
	v_mfma_f32_16x16x32_bf16 v[22:25], v[140:143], v[236:239], v[22:25]
	v_mfma_f32_16x16x32_bf16 v[14:17], v[152:155], v[236:239], v[14:17]
	v_mfma_f32_16x16x32_bf16 v[14:17], v[156:159], v[240:243], v[14:17]
	v_mfma_f32_16x16x32_bf16 v[30:33], v[156:159], v[232:235], v[30:33]
	v_mfma_f32_16x16x32_bf16 v[30:33], v[152:155], v[228:231], v[30:33]
	v_mfma_f32_16x16x32_bf16 v[46:49], v[152:155], v[202:205], v[46:49]
	v_mfma_f32_16x16x32_bf16 v[46:49], v[156:159], v[206:209], v[46:49]
	v_mfma_f32_16x16x32_bf16 v[58:61], v[156:159], v[198:201], v[58:61]
	v_mfma_f32_16x16x32_bf16 v[58:61], v[152:155], v[194:197], v[58:61]
	v_mfma_f32_16x16x32_bf16 v[50:53], v[160:163], v[194:197], v[50:53]
	v_mfma_f32_16x16x32_bf16 v[50:53], v[164:167], v[198:201], v[50:53]
	v_mfma_f32_16x16x32_bf16 v[34:37], v[164:167], v[206:209], v[34:37]
	v_mfma_f32_16x16x32_bf16 v[34:37], v[160:163], v[202:205], v[34:37]
	v_mfma_f32_16x16x32_bf16 v[18:21], v[160:163], v[228:231], v[18:21]
	v_mfma_f32_16x16x32_bf16 v[18:21], v[164:167], v[232:235], v[18:21]
	v_mfma_f32_16x16x32_bf16 v[6:9], v[164:167], v[240:243], v[6:9]
	v_mfma_f32_16x16x32_bf16 v[6:9], v[160:163], v[236:239], v[6:9]
	v_mfma_f32_16x16x32_bf16 v[2:5], v[168:171], v[236:239], v[2:5]
	v_mfma_f32_16x16x32_bf16 v[2:5], v[190:193], v[240:243], v[2:5]
	v_mfma_f32_16x16x32_bf16 v[10:13], v[190:193], v[232:235], v[10:13]
	v_mfma_f32_16x16x32_bf16 v[10:13], v[168:171], v[228:231], v[10:13]
	v_mfma_f32_16x16x32_bf16 v[26:29], v[168:171], v[202:205], v[26:29]
	v_mfma_f32_16x16x32_bf16 v[26:29], v[190:193], v[206:209], v[26:29]
	v_mfma_f32_16x16x32_bf16 v[42:45], v[190:193], v[198:201], v[42:45]
	v_mfma_f32_16x16x32_bf16 v[42:45], v[168:171], v[194:197], v[42:45]
	s_barrier
	s_setprio 0
	s_add_i32 s49, 0, 0x18000
	s_add_i32 s50, 0, 0x1c000
	v_add_u32_e32 v156, s49, v145
	v_add_u32_e32 v175, s50, v145
	ds_read_b128 v[140:143], v156
	ds_read_b128 v[148:151], v156 offset:1024
	ds_read_b128 v[152:155], v156 offset:2048
	ds_read_b128 v[156:159], v156 offset:3072
	ds_read_b128 v[160:163], v175
	ds_read_b128 v[164:167], v175 offset:1024
	ds_read_b128 v[168:171], v175 offset:2048
	ds_read_b128 v[190:193], v175 offset:3072
	s_add_u32 s24, s24, 0x100000
	s_addc_u32 s25, s25, 0
	s_mov_b32 m0, s37
	v_lshl_add_u64 v[244:245], s[24:25], 0, v[134:135]
	ds_read_b128 v[194:197], v147 offset:32768
	ds_read_b128 v[198:201], v147 offset:33792
	ds_read_b128 v[202:205], v147 offset:34816
	ds_read_b128 v[206:209], v147 offset:35840
	ds_read_b128 v[228:231], v147 offset:36864
	ds_read_b128 v[232:235], v147 offset:37888
	ds_read_b128 v[236:239], v147 offset:38912
	ds_read_b128 v[240:243], v147 offset:39936
	global_load_lds_dwordx4 v[244:245], off
	v_lshl_add_u64 v[244:245], s[24:25], 0, v[132:133]
	s_mov_b32 m0, s38
	s_nop 0
	global_load_lds_dwordx4 v[244:245], off
	s_waitcnt vmcnt(8)
	s_waitcnt lgkmcnt(0)
	s_setprio 1
	s_barrier
	v_mfma_f32_16x16x32_bf16 v[126:129], v[140:143], v[194:197], v[126:129]
	v_mfma_f32_16x16x32_bf16 v[126:129], v[148:151], v[198:201], v[126:129]
	v_mfma_f32_16x16x32_bf16 v[118:121], v[148:151], v[206:209], v[118:121]
	v_mfma_f32_16x16x32_bf16 v[118:121], v[140:143], v[202:205], v[118:121]
	v_mfma_f32_16x16x32_bf16 v[102:105], v[140:143], v[228:231], v[102:105]
	v_mfma_f32_16x16x32_bf16 v[102:105], v[148:151], v[232:235], v[102:105]
	v_mfma_f32_16x16x32_bf16 v[86:89], v[148:151], v[240:243], v[86:89]
	v_mfma_f32_16x16x32_bf16 v[86:89], v[140:143], v[236:239], v[86:89]
	v_mfma_f32_16x16x32_bf16 v[78:81], v[152:155], v[236:239], v[78:81]
	v_mfma_f32_16x16x32_bf16 v[78:81], v[156:159], v[240:243], v[78:81]
	v_mfma_f32_16x16x32_bf16 v[94:97], v[156:159], v[232:235], v[94:97]
	v_mfma_f32_16x16x32_bf16 v[94:97], v[152:155], v[228:231], v[94:97]
	v_mfma_f32_16x16x32_bf16 v[110:113], v[152:155], v[202:205], v[110:113]
	v_mfma_f32_16x16x32_bf16 v[110:113], v[156:159], v[206:209], v[110:113]
	v_mfma_f32_16x16x32_bf16 v[122:125], v[156:159], v[198:201], v[122:125]
	v_mfma_f32_16x16x32_bf16 v[122:125], v[152:155], v[194:197], v[122:125]
	v_mfma_f32_16x16x32_bf16 v[114:117], v[160:163], v[194:197], v[114:117]
	v_mfma_f32_16x16x32_bf16 v[114:117], v[164:167], v[198:201], v[114:117]
	v_mfma_f32_16x16x32_bf16 v[98:101], v[164:167], v[206:209], v[98:101]
	v_mfma_f32_16x16x32_bf16 v[98:101], v[160:163], v[202:205], v[98:101]
	v_mfma_f32_16x16x32_bf16 v[82:85], v[160:163], v[228:231], v[82:85]
	v_mfma_f32_16x16x32_bf16 v[82:85], v[164:167], v[232:235], v[82:85]
	v_mfma_f32_16x16x32_bf16 v[70:73], v[164:167], v[240:243], v[70:73]
	v_mfma_f32_16x16x32_bf16 v[70:73], v[160:163], v[236:239], v[70:73]
	v_mfma_f32_16x16x32_bf16 v[66:69], v[168:171], v[236:239], v[66:69]
	v_mfma_f32_16x16x32_bf16 v[66:69], v[190:193], v[240:243], v[66:69]
	v_mfma_f32_16x16x32_bf16 v[74:77], v[190:193], v[232:235], v[74:77]
	v_mfma_f32_16x16x32_bf16 v[74:77], v[168:171], v[228:231], v[74:77]
	v_mfma_f32_16x16x32_bf16 v[90:93], v[168:171], v[202:205], v[90:93]
	v_mfma_f32_16x16x32_bf16 v[90:93], v[190:193], v[206:209], v[90:93]
	v_mfma_f32_16x16x32_bf16 v[106:109], v[190:193], v[198:201], v[106:109]
	v_mfma_f32_16x16x32_bf16 v[106:109], v[168:171], v[194:197], v[106:109]
	s_barrier
	s_setprio 0
	s_add_i32 s24, s49, s26
	v_lshl_add_u64 v[172:173], v[172:173], 0, s[34:35]
	s_mov_b32 m0, s24
	ds_read_b128 v[194:197], v147 offset:49152
	ds_read_b128 v[198:201], v147 offset:50176
	ds_read_b128 v[202:205], v147 offset:51200
	ds_read_b128 v[206:209], v147 offset:52224
	ds_read_b128 v[228:231], v147 offset:53248
	ds_read_b128 v[232:235], v147 offset:54272
	ds_read_b128 v[236:239], v147 offset:55296
	ds_read_b128 v[240:243], v147 offset:56320
	global_load_lds_dwordx4 v[172:173], off
	s_add_i32 m0, s24, 0x2000
	s_add_u32 s22, s22, 0x100080
	v_lshl_add_u64 v[172:173], v[178:179], 0, s[34:35]
	s_addc_u32 s23, s23, 0
	s_add_i32 s24, s50, s26
	global_load_lds_dwordx4 v[172:173], off
	v_lshl_add_u64 v[172:173], s[22:23], 0, v[0:1]
	s_mov_b32 m0, s24
	s_nop 0
	global_load_lds_dwordx4 v[172:173], off
	v_lshl_add_u64 v[172:173], s[22:23], 0, v[130:131]
	s_add_i32 m0, s24, 0x2000
	s_nop 0
	global_load_lds_dwordx4 v[172:173], off
	v_lshl_add_u64 v[172:173], v[180:181], 0, s[34:35]
	s_mov_b32 m0, s39
	s_nop 0
	global_load_lds_dwordx4 v[172:173], off
	v_lshl_add_u64 v[172:173], v[210:211], 0, s[34:35]
	s_mov_b32 m0, s40
	s_nop 0
	global_load_lds_dwordx4 v[172:173], off
	s_waitcnt vmcnt(8)
	s_waitcnt lgkmcnt(0)
	s_setprio 1
	s_barrier
	v_mfma_f32_16x16x32_bf16 v[62:65], v[140:143], v[194:197], v[62:65]
	v_mfma_f32_16x16x32_bf16 v[62:65], v[148:151], v[198:201], v[62:65]
	v_mfma_f32_16x16x32_bf16 v[54:57], v[148:151], v[206:209], v[54:57]
	v_mfma_f32_16x16x32_bf16 v[54:57], v[140:143], v[202:205], v[54:57]
	v_mfma_f32_16x16x32_bf16 v[38:41], v[140:143], v[228:231], v[38:41]
	v_mfma_f32_16x16x32_bf16 v[38:41], v[148:151], v[232:235], v[38:41]
	v_mfma_f32_16x16x32_bf16 v[22:25], v[148:151], v[240:243], v[22:25]
	v_mfma_f32_16x16x32_bf16 v[22:25], v[140:143], v[236:239], v[22:25]
	v_mfma_f32_16x16x32_bf16 v[14:17], v[152:155], v[236:239], v[14:17]
	v_mfma_f32_16x16x32_bf16 v[14:17], v[156:159], v[240:243], v[14:17]
	v_mfma_f32_16x16x32_bf16 v[30:33], v[156:159], v[232:235], v[30:33]
	v_mfma_f32_16x16x32_bf16 v[30:33], v[152:155], v[228:231], v[30:33]
	v_mfma_f32_16x16x32_bf16 v[46:49], v[152:155], v[202:205], v[46:49]
	v_mfma_f32_16x16x32_bf16 v[46:49], v[156:159], v[206:209], v[46:49]
	v_mfma_f32_16x16x32_bf16 v[58:61], v[156:159], v[198:201], v[58:61]
	v_mfma_f32_16x16x32_bf16 v[58:61], v[152:155], v[194:197], v[58:61]
	v_mfma_f32_16x16x32_bf16 v[50:53], v[160:163], v[194:197], v[50:53]
	v_mfma_f32_16x16x32_bf16 v[50:53], v[164:167], v[198:201], v[50:53]
	v_mfma_f32_16x16x32_bf16 v[34:37], v[164:167], v[206:209], v[34:37]
	v_mfma_f32_16x16x32_bf16 v[34:37], v[160:163], v[202:205], v[34:37]
	v_mfma_f32_16x16x32_bf16 v[18:21], v[160:163], v[228:231], v[18:21]
	v_mfma_f32_16x16x32_bf16 v[18:21], v[164:167], v[232:235], v[18:21]
	v_mfma_f32_16x16x32_bf16 v[6:9], v[164:167], v[240:243], v[6:9]
	v_mfma_f32_16x16x32_bf16 v[6:9], v[160:163], v[236:239], v[6:9]
	v_mfma_f32_16x16x32_bf16 v[2:5], v[168:171], v[236:239], v[2:5]
	v_mfma_f32_16x16x32_bf16 v[2:5], v[190:193], v[240:243], v[2:5]
	v_mfma_f32_16x16x32_bf16 v[10:13], v[190:193], v[232:235], v[10:13]
	v_mfma_f32_16x16x32_bf16 v[10:13], v[168:171], v[228:231], v[10:13]
	v_mfma_f32_16x16x32_bf16 v[26:29], v[168:171], v[202:205], v[26:29]
	v_mfma_f32_16x16x32_bf16 v[26:29], v[190:193], v[206:209], v[26:29]
	v_mfma_f32_16x16x32_bf16 v[42:45], v[190:193], v[198:201], v[42:45]
	v_mfma_f32_16x16x32_bf16 v[42:45], v[168:171], v[194:197], v[42:45]
	s_barrier
	s_setprio 0
	s_add_i32 s48, s48, 2
	s_add_u32 s18, s18, 0x100
	s_addc_u32 s19, s19, 0
	s_add_u32 s46, s46, 0x100
	s_addc_u32 s47, s47, 0
	s_cmp_gt_u32 s48, 61
	s_cbranch_scc0 .LBB0_139
	s_and_b64 vcc, exec, s[4:5]
	s_cbranch_vccz .LBB0_142
	s_barrier

.LBB0_575:
	s_add_u32 s22, s18, 0xfff00080
	s_addc_u32 s23, s19, -1
	s_add_i32 s53, 0, 0x10000
	s_cmp_eq_u32 s52, 60
	s_cselect_b32 s25, s9, s23
	s_cselect_b32 s24, s48, s22
	v_add_u32_e32 v140, s53, v143
	s_cselect_b32 s23, s7, s51
	s_cselect_b32 s22, s49, s50
	s_add_i32 s56, 0, 0x14000
	ds_read_b128 v[146:149], v140
	ds_read_b128 v[150:153], v140 offset:1024
	ds_read_b128 v[154:157], v140 offset:2048
	ds_read_b128 v[158:161], v140 offset:3072
	v_add_u32_e32 v140, s56, v143
	ds_read_b128 v[162:165], v140
	ds_read_b128 v[166:169], v140 offset:1024
	ds_read_b128 v[170:173], v140 offset:2048
	ds_read_b128 v[178:181], v140 offset:3072
	v_lshl_add_u64 v[140:141], s[18:19], 0, v[136:137]
	s_add_i32 m0, s39, 0xc000
	ds_read_b128 v[190:193], v145
	ds_read_b128 v[194:197], v145 offset:1024
	ds_read_b128 v[198:201], v145 offset:2048
	ds_read_b128 v[202:205], v145 offset:3072
	ds_read_b128 v[206:209], v145 offset:4096
	ds_read_b128 v[228:231], v145 offset:5120
	ds_read_b128 v[232:235], v145 offset:6144
	ds_read_b128 v[236:239], v145 offset:7168
	global_load_lds_dwordx4 v[140:141], off
	v_lshl_add_u64 v[140:141], s[18:19], 0, v[138:139]
	s_add_i32 m0, s39, 0xe000
	s_nop 0
	global_load_lds_dwordx4 v[140:141], off
	s_cmp_lg_u32 s52, 0xfffffffe
	s_cbranch_scc1 .Low_4_norm
	s_cmp_eq_u32 s45, 1
	s_cbranch_scc1 .Low_4_norm
	s_waitcnt vmcnt(24)
	s_branch .Low_4_done

.Low_4_done:
	s_waitcnt lgkmcnt(0)
	s_setprio 1
	s_barrier
	v_mfma_f32_16x16x32_bf16 v[126:129], v[146:149], v[190:193], v[126:129]
	v_mfma_f32_16x16x32_bf16 v[126:129], v[150:153], v[194:197], v[126:129]
	v_mfma_f32_16x16x32_bf16 v[118:121], v[150:153], v[202:205], v[118:121]
	v_mfma_f32_16x16x32_bf16 v[118:121], v[146:149], v[198:201], v[118:121]
	v_mfma_f32_16x16x32_bf16 v[102:105], v[146:149], v[206:209], v[102:105]
	v_mfma_f32_16x16x32_bf16 v[102:105], v[150:153], v[228:231], v[102:105]
	v_mfma_f32_16x16x32_bf16 v[86:89], v[150:153], v[236:239], v[86:89]
	v_mfma_f32_16x16x32_bf16 v[86:89], v[146:149], v[232:235], v[86:89]
	v_mfma_f32_16x16x32_bf16 v[78:81], v[154:157], v[232:235], v[78:81]
	v_mfma_f32_16x16x32_bf16 v[78:81], v[158:161], v[236:239], v[78:81]
	v_mfma_f32_16x16x32_bf16 v[94:97], v[158:161], v[228:231], v[94:97]
	v_mfma_f32_16x16x32_bf16 v[94:97], v[154:157], v[206:209], v[94:97]
	v_mfma_f32_16x16x32_bf16 v[110:113], v[154:157], v[198:201], v[110:113]
	v_mfma_f32_16x16x32_bf16 v[110:113], v[158:161], v[202:205], v[110:113]
	v_mfma_f32_16x16x32_bf16 v[122:125], v[158:161], v[194:197], v[122:125]
	v_mfma_f32_16x16x32_bf16 v[122:125], v[154:157], v[190:193], v[122:125]
	v_mfma_f32_16x16x32_bf16 v[114:117], v[162:165], v[190:193], v[114:117]
	v_mfma_f32_16x16x32_bf16 v[114:117], v[166:169], v[194:197], v[114:117]
	v_mfma_f32_16x16x32_bf16 v[98:101], v[166:169], v[202:205], v[98:101]
	v_mfma_f32_16x16x32_bf16 v[98:101], v[162:165], v[198:201], v[98:101]
	v_mfma_f32_16x16x32_bf16 v[82:85], v[162:165], v[206:209], v[82:85]
	v_mfma_f32_16x16x32_bf16 v[82:85], v[166:169], v[228:231], v[82:85]
	v_mfma_f32_16x16x32_bf16 v[70:73], v[166:169], v[236:239], v[70:73]
	v_mfma_f32_16x16x32_bf16 v[70:73], v[162:165], v[232:235], v[70:73]
	v_mfma_f32_16x16x32_bf16 v[66:69], v[170:173], v[232:235], v[66:69]
	v_mfma_f32_16x16x32_bf16 v[66:69], v[178:181], v[236:239], v[66:69]
	v_mfma_f32_16x16x32_bf16 v[74:77], v[178:181], v[228:231], v[74:77]
	v_mfma_f32_16x16x32_bf16 v[74:77], v[170:173], v[206:209], v[74:77]
	v_mfma_f32_16x16x32_bf16 v[90:93], v[170:173], v[198:201], v[90:93]
	v_mfma_f32_16x16x32_bf16 v[90:93], v[178:181], v[202:205], v[90:93]
	v_mfma_f32_16x16x32_bf16 v[106:109], v[178:181], v[194:197], v[106:109]
	v_mfma_f32_16x16x32_bf16 v[106:109], v[170:173], v[190:193], v[106:109]
	s_barrier
	s_setprio 0
	s_add_i32 s53, s53, s38
	v_lshl_add_u64 v[140:141], s[22:23], 0, v[0:1]
	s_mov_b32 m0, s53
	ds_read_b128 v[190:193], v145 offset:16384
	ds_read_b128 v[194:197], v145 offset:17408
	ds_read_b128 v[198:201], v145 offset:18432
	ds_read_b128 v[202:205], v145 offset:19456
	ds_read_b128 v[206:209], v145 offset:20480
	ds_read_b128 v[228:231], v145 offset:21504
	ds_read_b128 v[232:235], v145 offset:22528
	ds_read_b128 v[236:239], v145 offset:23552
	global_load_lds_dwordx4 v[140:141], off
	s_add_i32 m0, s53, 0x2000
	s_add_u32 s54, s22, 0x100000
	v_lshl_add_u64 v[186:187], s[22:23], 0, v[130:131]
	s_addc_u32 s55, s23, 0
	s_add_i32 s53, s56, s38
	global_load_lds_dwordx4 v[186:187], off
	v_lshl_add_u64 v[188:189], s[54:55], 0, v[0:1]
	s_mov_b32 m0, s53
	v_lshl_add_u64 v[210:211], s[24:25], 0, v[132:133]
	global_load_lds_dwordx4 v[188:189], off
	v_lshl_add_u64 v[188:189], s[54:55], 0, v[130:131]
	s_add_i32 m0, s53, 0x2000
	s_nop 0
	global_load_lds_dwordx4 v[188:189], off
	v_lshl_add_u64 v[188:189], s[24:25], 0, v[134:135]
	s_mov_b32 m0, s39
	s_nop 0
	global_load_lds_dwordx4 v[188:189], off
	s_mov_b32 m0, s40
	s_nop 0
	global_load_lds_dwordx4 v[210:211], off
	s_cmp_lg_u32 s52, 0xfffffffe
	s_cbranch_scc1 .Low_3_norm
	s_cmp_eq_u32 s45, 1
	s_cbranch_scc1 .Low_3_norm
	s_waitcnt vmcnt(24)
	s_branch .Low_3_done

.Low_3_done:
	s_waitcnt lgkmcnt(0)
	s_setprio 1
	s_barrier
	v_mfma_f32_16x16x32_bf16 v[62:65], v[146:149], v[190:193], v[62:65]
	v_mfma_f32_16x16x32_bf16 v[62:65], v[150:153], v[194:197], v[62:65]
	v_mfma_f32_16x16x32_bf16 v[54:57], v[150:153], v[202:205], v[54:57]
	v_mfma_f32_16x16x32_bf16 v[54:57], v[146:149], v[198:201], v[54:57]
	v_mfma_f32_16x16x32_bf16 v[38:41], v[146:149], v[206:209], v[38:41]
	v_mfma_f32_16x16x32_bf16 v[38:41], v[150:153], v[228:231], v[38:41]
	v_mfma_f32_16x16x32_bf16 v[22:25], v[150:153], v[236:239], v[22:25]
	v_mfma_f32_16x16x32_bf16 v[22:25], v[146:149], v[232:235], v[22:25]
	v_mfma_f32_16x16x32_bf16 v[14:17], v[154:157], v[232:235], v[14:17]
	v_mfma_f32_16x16x32_bf16 v[14:17], v[158:161], v[236:239], v[14:17]
	v_mfma_f32_16x16x32_bf16 v[30:33], v[158:161], v[228:231], v[30:33]
	v_mfma_f32_16x16x32_bf16 v[30:33], v[154:157], v[206:209], v[30:33]
	v_mfma_f32_16x16x32_bf16 v[46:49], v[154:157], v[198:201], v[46:49]
	v_mfma_f32_16x16x32_bf16 v[46:49], v[158:161], v[202:205], v[46:49]
	v_mfma_f32_16x16x32_bf16 v[58:61], v[158:161], v[194:197], v[58:61]
	v_mfma_f32_16x16x32_bf16 v[58:61], v[154:157], v[190:193], v[58:61]
	v_mfma_f32_16x16x32_bf16 v[50:53], v[162:165], v[190:193], v[50:53]
	v_mfma_f32_16x16x32_bf16 v[50:53], v[166:169], v[194:197], v[50:53]
	v_mfma_f32_16x16x32_bf16 v[34:37], v[166:169], v[202:205], v[34:37]
	v_mfma_f32_16x16x32_bf16 v[34:37], v[162:165], v[198:201], v[34:37]
	v_mfma_f32_16x16x32_bf16 v[18:21], v[162:165], v[206:209], v[18:21]
	v_mfma_f32_16x16x32_bf16 v[18:21], v[166:169], v[228:231], v[18:21]
	v_mfma_f32_16x16x32_bf16 v[6:9], v[166:169], v[236:239], v[6:9]
	v_mfma_f32_16x16x32_bf16 v[6:9], v[162:165], v[232:235], v[6:9]
	v_mfma_f32_16x16x32_bf16 v[2:5], v[170:173], v[232:235], v[2:5]
	v_mfma_f32_16x16x32_bf16 v[2:5], v[178:181], v[236:239], v[2:5]
	v_mfma_f32_16x16x32_bf16 v[10:13], v[178:181], v[228:231], v[10:13]
	v_mfma_f32_16x16x32_bf16 v[10:13], v[170:173], v[206:209], v[10:13]
	v_mfma_f32_16x16x32_bf16 v[26:29], v[170:173], v[198:201], v[26:29]
	v_mfma_f32_16x16x32_bf16 v[26:29], v[178:181], v[202:205], v[26:29]
	v_mfma_f32_16x16x32_bf16 v[42:45], v[178:181], v[194:197], v[42:45]
	v_mfma_f32_16x16x32_bf16 v[42:45], v[170:173], v[190:193], v[42:45]
	s_barrier
	s_setprio 0
	s_add_i32 s53, 0, 0x18000
	s_add_i32 s54, 0, 0x1c000
	v_add_u32_e32 v158, s53, v143
	v_add_u32_e32 v175, s54, v143
	ds_read_b128 v[146:149], v158
	ds_read_b128 v[150:153], v158 offset:1024
	ds_read_b128 v[154:157], v158 offset:2048
	ds_read_b128 v[158:161], v158 offset:3072
	ds_read_b128 v[162:165], v175
	ds_read_b128 v[166:169], v175 offset:1024
	ds_read_b128 v[170:173], v175 offset:2048
	ds_read_b128 v[178:181], v175 offset:3072
	s_add_u32 s24, s24, 0x100000
	s_addc_u32 s25, s25, 0
	s_mov_b32 m0, s41
	v_lshl_add_u64 v[226:227], s[24:25], 0, v[134:135]
	ds_read_b128 v[190:193], v145 offset:32768
	ds_read_b128 v[194:197], v145 offset:33792
	ds_read_b128 v[198:201], v145 offset:34816
	ds_read_b128 v[202:205], v145 offset:35840
	ds_read_b128 v[206:209], v145 offset:36864
	ds_read_b128 v[228:231], v145 offset:37888
	ds_read_b128 v[232:235], v145 offset:38912
	ds_read_b128 v[236:239], v145 offset:39936
	global_load_lds_dwordx4 v[226:227], off
	v_lshl_add_u64 v[226:227], s[24:25], 0, v[132:133]
	s_mov_b32 m0, s42
	s_nop 0
	global_load_lds_dwordx4 v[226:227], off
	s_waitcnt vmcnt(8)
	s_waitcnt lgkmcnt(0)
	s_setprio 1
	s_barrier
	v_mfma_f32_16x16x32_bf16 v[126:129], v[146:149], v[190:193], v[126:129]
	v_mfma_f32_16x16x32_bf16 v[126:129], v[150:153], v[194:197], v[126:129]
	v_mfma_f32_16x16x32_bf16 v[118:121], v[150:153], v[202:205], v[118:121]
	v_mfma_f32_16x16x32_bf16 v[118:121], v[146:149], v[198:201], v[118:121]
	v_mfma_f32_16x16x32_bf16 v[102:105], v[146:149], v[206:209], v[102:105]
	v_mfma_f32_16x16x32_bf16 v[102:105], v[150:153], v[228:231], v[102:105]
	v_mfma_f32_16x16x32_bf16 v[86:89], v[150:153], v[236:239], v[86:89]
	v_mfma_f32_16x16x32_bf16 v[86:89], v[146:149], v[232:235], v[86:89]
	v_mfma_f32_16x16x32_bf16 v[78:81], v[154:157], v[232:235], v[78:81]
	v_mfma_f32_16x16x32_bf16 v[78:81], v[158:161], v[236:239], v[78:81]
	v_mfma_f32_16x16x32_bf16 v[94:97], v[158:161], v[228:231], v[94:97]
	v_mfma_f32_16x16x32_bf16 v[94:97], v[154:157], v[206:209], v[94:97]
	v_mfma_f32_16x16x32_bf16 v[110:113], v[154:157], v[198:201], v[110:113]
	v_mfma_f32_16x16x32_bf16 v[110:113], v[158:161], v[202:205], v[110:113]
	v_mfma_f32_16x16x32_bf16 v[122:125], v[158:161], v[194:197], v[122:125]
	v_mfma_f32_16x16x32_bf16 v[122:125], v[154:157], v[190:193], v[122:125]
	v_mfma_f32_16x16x32_bf16 v[114:117], v[162:165], v[190:193], v[114:117]
	v_mfma_f32_16x16x32_bf16 v[114:117], v[166:169], v[194:197], v[114:117]
	v_mfma_f32_16x16x32_bf16 v[98:101], v[166:169], v[202:205], v[98:101]
	v_mfma_f32_16x16x32_bf16 v[98:101], v[162:165], v[198:201], v[98:101]
	v_mfma_f32_16x16x32_bf16 v[82:85], v[162:165], v[206:209], v[82:85]
	v_mfma_f32_16x16x32_bf16 v[82:85], v[166:169], v[228:231], v[82:85]
	v_mfma_f32_16x16x32_bf16 v[70:73], v[166:169], v[236:239], v[70:73]
	v_mfma_f32_16x16x32_bf16 v[70:73], v[162:165], v[232:235], v[70:73]
	v_mfma_f32_16x16x32_bf16 v[66:69], v[170:173], v[232:235], v[66:69]
	v_mfma_f32_16x16x32_bf16 v[66:69], v[178:181], v[236:239], v[66:69]
	v_mfma_f32_16x16x32_bf16 v[74:77], v[178:181], v[228:231], v[74:77]
	v_mfma_f32_16x16x32_bf16 v[74:77], v[170:173], v[206:209], v[74:77]
	v_mfma_f32_16x16x32_bf16 v[90:93], v[170:173], v[198:201], v[90:93]
	v_mfma_f32_16x16x32_bf16 v[90:93], v[178:181], v[202:205], v[90:93]
	v_mfma_f32_16x16x32_bf16 v[106:109], v[178:181], v[194:197], v[106:109]
	v_mfma_f32_16x16x32_bf16 v[106:109], v[170:173], v[190:193], v[106:109]
	s_barrier
	s_setprio 0
	s_add_i32 s24, s53, s38
	v_lshl_add_u64 v[140:141], v[140:141], 0, s[34:35]
	s_mov_b32 m0, s24
	ds_read_b128 v[190:193], v145 offset:49152
	ds_read_b128 v[194:197], v145 offset:50176
	ds_read_b128 v[198:201], v145 offset:51200
	ds_read_b128 v[202:205], v145 offset:52224
	ds_read_b128 v[206:209], v145 offset:53248
	ds_read_b128 v[228:231], v145 offset:54272
	ds_read_b128 v[232:235], v145 offset:55296
	ds_read_b128 v[236:239], v145 offset:56320
	global_load_lds_dwordx4 v[140:141], off
	s_add_i32 m0, s24, 0x2000
	s_add_u32 s22, s22, 0x100080
	v_lshl_add_u64 v[140:141], v[186:187], 0, s[34:35]
	s_addc_u32 s23, s23, 0
	s_add_i32 s24, s54, s38
	global_load_lds_dwordx4 v[140:141], off
	v_lshl_add_u64 v[140:141], s[22:23], 0, v[0:1]
	s_mov_b32 m0, s24
	s_nop 0
	global_load_lds_dwordx4 v[140:141], off
	v_lshl_add_u64 v[140:141], s[22:23], 0, v[130:131]
	s_add_i32 m0, s24, 0x2000
	s_nop 0
	global_load_lds_dwordx4 v[140:141], off
	v_lshl_add_u64 v[140:141], v[188:189], 0, s[34:35]
	s_mov_b32 m0, s43
	s_nop 0
	global_load_lds_dwordx4 v[140:141], off
	v_lshl_add_u64 v[140:141], v[210:211], 0, s[34:35]
	s_mov_b32 m0, s44
	s_nop 0
	global_load_lds_dwordx4 v[140:141], off
	s_waitcnt vmcnt(8)
	s_waitcnt lgkmcnt(0)
	s_setprio 1
	s_barrier
	v_mfma_f32_16x16x32_bf16 v[62:65], v[146:149], v[190:193], v[62:65]
	v_mfma_f32_16x16x32_bf16 v[62:65], v[150:153], v[194:197], v[62:65]
	v_mfma_f32_16x16x32_bf16 v[54:57], v[150:153], v[202:205], v[54:57]
	v_mfma_f32_16x16x32_bf16 v[54:57], v[146:149], v[198:201], v[54:57]
	v_mfma_f32_16x16x32_bf16 v[38:41], v[146:149], v[206:209], v[38:41]
	v_mfma_f32_16x16x32_bf16 v[38:41], v[150:153], v[228:231], v[38:41]
	v_mfma_f32_16x16x32_bf16 v[22:25], v[150:153], v[236:239], v[22:25]
	v_mfma_f32_16x16x32_bf16 v[22:25], v[146:149], v[232:235], v[22:25]
	v_mfma_f32_16x16x32_bf16 v[14:17], v[154:157], v[232:235], v[14:17]
	v_mfma_f32_16x16x32_bf16 v[14:17], v[158:161], v[236:239], v[14:17]
	v_mfma_f32_16x16x32_bf16 v[30:33], v[158:161], v[228:231], v[30:33]
	v_mfma_f32_16x16x32_bf16 v[30:33], v[154:157], v[206:209], v[30:33]
	v_mfma_f32_16x16x32_bf16 v[46:49], v[154:157], v[198:201], v[46:49]
	v_mfma_f32_16x16x32_bf16 v[46:49], v[158:161], v[202:205], v[46:49]
	v_mfma_f32_16x16x32_bf16 v[58:61], v[158:161], v[194:197], v[58:61]
	v_mfma_f32_16x16x32_bf16 v[58:61], v[154:157], v[190:193], v[58:61]
	v_mfma_f32_16x16x32_bf16 v[50:53], v[162:165], v[190:193], v[50:53]
	v_mfma_f32_16x16x32_bf16 v[50:53], v[166:169], v[194:197], v[50:53]
	v_mfma_f32_16x16x32_bf16 v[34:37], v[166:169], v[202:205], v[34:37]
	v_mfma_f32_16x16x32_bf16 v[34:37], v[162:165], v[198:201], v[34:37]
	v_mfma_f32_16x16x32_bf16 v[18:21], v[162:165], v[206:209], v[18:21]
	v_mfma_f32_16x16x32_bf16 v[18:21], v[166:169], v[228:231], v[18:21]
	v_mfma_f32_16x16x32_bf16 v[6:9], v[166:169], v[236:239], v[6:9]
	v_mfma_f32_16x16x32_bf16 v[6:9], v[162:165], v[232:235], v[6:9]
	v_mfma_f32_16x16x32_bf16 v[2:5], v[170:173], v[232:235], v[2:5]
	v_mfma_f32_16x16x32_bf16 v[2:5], v[178:181], v[236:239], v[2:5]
	v_mfma_f32_16x16x32_bf16 v[10:13], v[178:181], v[228:231], v[10:13]
	v_mfma_f32_16x16x32_bf16 v[10:13], v[170:173], v[206:209], v[10:13]
	v_mfma_f32_16x16x32_bf16 v[26:29], v[170:173], v[198:201], v[26:29]
	v_mfma_f32_16x16x32_bf16 v[26:29], v[178:181], v[202:205], v[26:29]
	v_mfma_f32_16x16x32_bf16 v[42:45], v[178:181], v[194:197], v[42:45]
	v_mfma_f32_16x16x32_bf16 v[42:45], v[170:173], v[190:193], v[42:45]
	s_barrier
	s_setprio 0
	s_add_i32 s52, s52, 2
	s_add_u32 s18, s18, 0x100
	s_addc_u32 s19, s19, 0
	s_add_u32 s50, s50, 0x100
	s_addc_u32 s51, s51, 0
	s_cmp_gt_u32 s52, 61
	s_cbranch_scc0 .LBB0_575
	s_and_b64 vcc, exec, s[4:5]
	s_cbranch_vccz .LBB0_578
	s_barrier

.LBB0_721:
	s_add_u32 s18, s16, 0xfff00080
	s_addc_u32 s19, s17, -1
	s_add_i32 s53, 0, 0x10000
	s_cmp_eq_u32 s52, 60
	s_cselect_b32 s23, s7, s19
	s_cselect_b32 s22, s48, s18
	v_add_u32_e32 v140, s53, v143
	s_cselect_b32 s19, s5, s51
	s_cselect_b32 s18, s49, s50
	s_add_i32 s56, 0, 0x14000
	ds_read_b128 v[146:149], v140
	ds_read_b128 v[150:153], v140 offset:1024
	ds_read_b128 v[154:157], v140 offset:2048
	ds_read_b128 v[158:161], v140 offset:3072
	v_add_u32_e32 v140, s56, v143
	ds_read_b128 v[162:165], v140
	ds_read_b128 v[166:169], v140 offset:1024
	ds_read_b128 v[170:173], v140 offset:2048
	ds_read_b128 v[178:181], v140 offset:3072
	v_lshl_add_u64 v[140:141], s[16:17], 0, v[136:137]
	s_add_i32 m0, s31, 0xc000
	ds_read_b128 v[190:193], v145
	ds_read_b128 v[194:197], v145 offset:1024
	ds_read_b128 v[198:201], v145 offset:2048
	ds_read_b128 v[202:205], v145 offset:3072
	ds_read_b128 v[206:209], v145 offset:4096
	ds_read_b128 v[228:231], v145 offset:5120
	ds_read_b128 v[232:235], v145 offset:6144
	ds_read_b128 v[236:239], v145 offset:7168
	global_load_lds_dwordx4 v[140:141], off
	v_lshl_add_u64 v[140:141], s[16:17], 0, v[138:139]
	s_add_i32 m0, s31, 0xe000
	s_nop 0
	global_load_lds_dwordx4 v[140:141], off
	s_cmp_lg_u32 s52, 0xfffffffe
	s_cbranch_scc1 .Low_6_norm
	s_cmp_eq_u32 s45, 1
	s_cbranch_scc1 .Low_6_norm
	s_waitcnt vmcnt(16)
	s_branch .Low_6_done

.Low_6_done:
	s_waitcnt lgkmcnt(0)
	s_setprio 1
	s_barrier
	v_mfma_f32_16x16x32_bf16 v[126:129], v[146:149], v[190:193], v[126:129]
	v_mfma_f32_16x16x32_bf16 v[126:129], v[150:153], v[194:197], v[126:129]
	v_mfma_f32_16x16x32_bf16 v[110:113], v[150:153], v[202:205], v[110:113]
	v_mfma_f32_16x16x32_bf16 v[110:113], v[146:149], v[198:201], v[110:113]
	v_mfma_f32_16x16x32_bf16 v[94:97], v[146:149], v[206:209], v[94:97]
	v_mfma_f32_16x16x32_bf16 v[94:97], v[150:153], v[228:231], v[94:97]
	v_mfma_f32_16x16x32_bf16 v[78:81], v[150:153], v[236:239], v[78:81]
	v_mfma_f32_16x16x32_bf16 v[78:81], v[146:149], v[232:235], v[78:81]
	v_mfma_f32_16x16x32_bf16 v[70:73], v[154:157], v[232:235], v[70:73]
	v_mfma_f32_16x16x32_bf16 v[70:73], v[158:161], v[236:239], v[70:73]
	v_mfma_f32_16x16x32_bf16 v[86:89], v[158:161], v[228:231], v[86:89]
	v_mfma_f32_16x16x32_bf16 v[86:89], v[154:157], v[206:209], v[86:89]
	v_mfma_f32_16x16x32_bf16 v[102:105], v[154:157], v[198:201], v[102:105]
	v_mfma_f32_16x16x32_bf16 v[102:105], v[158:161], v[202:205], v[102:105]
	v_mfma_f32_16x16x32_bf16 v[118:121], v[158:161], v[194:197], v[118:121]
	v_mfma_f32_16x16x32_bf16 v[118:121], v[154:157], v[190:193], v[118:121]
	v_mfma_f32_16x16x32_bf16 v[122:125], v[162:165], v[190:193], v[122:125]
	v_mfma_f32_16x16x32_bf16 v[122:125], v[166:169], v[194:197], v[122:125]
	v_mfma_f32_16x16x32_bf16 v[106:109], v[166:169], v[202:205], v[106:109]
	v_mfma_f32_16x16x32_bf16 v[106:109], v[162:165], v[198:201], v[106:109]
	v_mfma_f32_16x16x32_bf16 v[90:93], v[162:165], v[206:209], v[90:93]
	v_mfma_f32_16x16x32_bf16 v[90:93], v[166:169], v[228:231], v[90:93]
	v_mfma_f32_16x16x32_bf16 v[74:77], v[166:169], v[236:239], v[74:77]
	v_mfma_f32_16x16x32_bf16 v[74:77], v[162:165], v[232:235], v[74:77]
	v_mfma_f32_16x16x32_bf16 v[66:69], v[170:173], v[232:235], v[66:69]
	v_mfma_f32_16x16x32_bf16 v[66:69], v[178:181], v[236:239], v[66:69]
	v_mfma_f32_16x16x32_bf16 v[82:85], v[178:181], v[228:231], v[82:85]
	v_mfma_f32_16x16x32_bf16 v[82:85], v[170:173], v[206:209], v[82:85]
	v_mfma_f32_16x16x32_bf16 v[98:101], v[170:173], v[198:201], v[98:101]
	v_mfma_f32_16x16x32_bf16 v[98:101], v[178:181], v[202:205], v[98:101]
	v_mfma_f32_16x16x32_bf16 v[114:117], v[178:181], v[194:197], v[114:117]
	v_mfma_f32_16x16x32_bf16 v[114:117], v[170:173], v[190:193], v[114:117]
	s_barrier
	s_setprio 0
	s_add_i32 s53, s53, s26
	v_lshl_add_u64 v[140:141], s[18:19], 0, v[0:1]
	s_mov_b32 m0, s53
	ds_read_b128 v[190:193], v145 offset:16384
	ds_read_b128 v[194:197], v145 offset:17408
	ds_read_b128 v[198:201], v145 offset:18432
	ds_read_b128 v[202:205], v145 offset:19456
	ds_read_b128 v[206:209], v145 offset:20480
	ds_read_b128 v[228:231], v145 offset:21504
	ds_read_b128 v[232:235], v145 offset:22528
	ds_read_b128 v[236:239], v145 offset:23552
	global_load_lds_dwordx4 v[140:141], off
	s_add_i32 m0, s53, 0x2000
	s_add_u32 s54, s18, 0x100000
	v_lshl_add_u64 v[186:187], s[18:19], 0, v[130:131]
	s_addc_u32 s55, s19, 0
	s_add_i32 s53, s56, s26
	global_load_lds_dwordx4 v[186:187], off
	v_lshl_add_u64 v[188:189], s[54:55], 0, v[0:1]
	s_mov_b32 m0, s53
	v_lshl_add_u64 v[210:211], s[22:23], 0, v[132:133]
	global_load_lds_dwordx4 v[188:189], off
	v_lshl_add_u64 v[188:189], s[54:55], 0, v[130:131]
	s_add_i32 m0, s53, 0x2000
	s_nop 0
	global_load_lds_dwordx4 v[188:189], off
	v_lshl_add_u64 v[188:189], s[22:23], 0, v[134:135]
	s_mov_b32 m0, s31
	s_nop 0
	global_load_lds_dwordx4 v[188:189], off
	s_mov_b32 m0, s40
	s_nop 0
	global_load_lds_dwordx4 v[210:211], off
	s_cmp_lg_u32 s52, 0xfffffffe
	s_cbranch_scc1 .Low_5_norm
	s_cmp_eq_u32 s45, 1
	s_cbranch_scc1 .Low_5_norm
	s_waitcnt vmcnt(16)
	s_branch .Low_5_done

.Low_5_done:
	s_waitcnt lgkmcnt(0)
	s_setprio 1
	s_barrier
	v_mfma_f32_16x16x32_bf16 v[62:65], v[146:149], v[190:193], v[62:65]
	v_mfma_f32_16x16x32_bf16 v[62:65], v[150:153], v[194:197], v[62:65]
	v_mfma_f32_16x16x32_bf16 v[46:49], v[150:153], v[202:205], v[46:49]
	v_mfma_f32_16x16x32_bf16 v[46:49], v[146:149], v[198:201], v[46:49]
	v_mfma_f32_16x16x32_bf16 v[30:33], v[146:149], v[206:209], v[30:33]
	v_mfma_f32_16x16x32_bf16 v[30:33], v[150:153], v[228:231], v[30:33]
	v_mfma_f32_16x16x32_bf16 v[14:17], v[150:153], v[236:239], v[14:17]
	v_mfma_f32_16x16x32_bf16 v[14:17], v[146:149], v[232:235], v[14:17]
	v_mfma_f32_16x16x32_bf16 v[6:9], v[154:157], v[232:235], v[6:9]
	v_mfma_f32_16x16x32_bf16 v[6:9], v[158:161], v[236:239], v[6:9]
	v_mfma_f32_16x16x32_bf16 v[22:25], v[158:161], v[228:231], v[22:25]
	v_mfma_f32_16x16x32_bf16 v[22:25], v[154:157], v[206:209], v[22:25]
	v_mfma_f32_16x16x32_bf16 v[38:41], v[154:157], v[198:201], v[38:41]
	v_mfma_f32_16x16x32_bf16 v[38:41], v[158:161], v[202:205], v[38:41]
	v_mfma_f32_16x16x32_bf16 v[54:57], v[158:161], v[194:197], v[54:57]
	v_mfma_f32_16x16x32_bf16 v[54:57], v[154:157], v[190:193], v[54:57]
	v_mfma_f32_16x16x32_bf16 v[58:61], v[162:165], v[190:193], v[58:61]
	v_mfma_f32_16x16x32_bf16 v[58:61], v[166:169], v[194:197], v[58:61]
	v_mfma_f32_16x16x32_bf16 v[42:45], v[166:169], v[202:205], v[42:45]
	v_mfma_f32_16x16x32_bf16 v[42:45], v[162:165], v[198:201], v[42:45]
	v_mfma_f32_16x16x32_bf16 v[26:29], v[162:165], v[206:209], v[26:29]
	v_mfma_f32_16x16x32_bf16 v[26:29], v[166:169], v[228:231], v[26:29]
	v_mfma_f32_16x16x32_bf16 v[10:13], v[166:169], v[236:239], v[10:13]
	v_mfma_f32_16x16x32_bf16 v[10:13], v[162:165], v[232:235], v[10:13]
	v_mfma_f32_16x16x32_bf16 v[2:5], v[170:173], v[232:235], v[2:5]
	v_mfma_f32_16x16x32_bf16 v[2:5], v[178:181], v[236:239], v[2:5]
	v_mfma_f32_16x16x32_bf16 v[18:21], v[178:181], v[228:231], v[18:21]
	v_mfma_f32_16x16x32_bf16 v[18:21], v[170:173], v[206:209], v[18:21]
	v_mfma_f32_16x16x32_bf16 v[34:37], v[170:173], v[198:201], v[34:37]
	v_mfma_f32_16x16x32_bf16 v[34:37], v[178:181], v[202:205], v[34:37]
	v_mfma_f32_16x16x32_bf16 v[50:53], v[178:181], v[194:197], v[50:53]
	v_mfma_f32_16x16x32_bf16 v[50:53], v[170:173], v[190:193], v[50:53]
	s_barrier
	s_setprio 0
	s_add_i32 s53, 0, 0x18000
	s_add_i32 s54, 0, 0x1c000
	v_add_u32_e32 v158, s53, v143
	v_add_u32_e32 v175, s54, v143
	ds_read_b128 v[146:149], v158
	ds_read_b128 v[150:153], v158 offset:1024
	ds_read_b128 v[154:157], v158 offset:2048
	ds_read_b128 v[158:161], v158 offset:3072
	ds_read_b128 v[162:165], v175
	ds_read_b128 v[166:169], v175 offset:1024
	ds_read_b128 v[170:173], v175 offset:2048
	ds_read_b128 v[178:181], v175 offset:3072
	s_add_u32 s22, s22, 0x100000
	s_addc_u32 s23, s23, 0
	s_mov_b32 m0, s41
	v_lshl_add_u64 v[226:227], s[22:23], 0, v[134:135]
	ds_read_b128 v[190:193], v145 offset:32768
	ds_read_b128 v[194:197], v145 offset:33792
	ds_read_b128 v[198:201], v145 offset:34816
	ds_read_b128 v[202:205], v145 offset:35840
	ds_read_b128 v[206:209], v145 offset:36864
	ds_read_b128 v[228:231], v145 offset:37888
	ds_read_b128 v[232:235], v145 offset:38912
	ds_read_b128 v[236:239], v145 offset:39936
	global_load_lds_dwordx4 v[226:227], off
	v_lshl_add_u64 v[226:227], s[22:23], 0, v[132:133]
	s_mov_b32 m0, s42
	s_nop 0
	global_load_lds_dwordx4 v[226:227], off
	s_waitcnt vmcnt(8)
	s_waitcnt lgkmcnt(0)
	s_setprio 1
	s_barrier
	v_mfma_f32_16x16x32_bf16 v[126:129], v[146:149], v[190:193], v[126:129]
	v_mfma_f32_16x16x32_bf16 v[126:129], v[150:153], v[194:197], v[126:129]
	v_mfma_f32_16x16x32_bf16 v[110:113], v[150:153], v[202:205], v[110:113]
	v_mfma_f32_16x16x32_bf16 v[110:113], v[146:149], v[198:201], v[110:113]
	v_mfma_f32_16x16x32_bf16 v[94:97], v[146:149], v[206:209], v[94:97]
	v_mfma_f32_16x16x32_bf16 v[94:97], v[150:153], v[228:231], v[94:97]
	v_mfma_f32_16x16x32_bf16 v[78:81], v[150:153], v[236:239], v[78:81]
	v_mfma_f32_16x16x32_bf16 v[78:81], v[146:149], v[232:235], v[78:81]
	v_mfma_f32_16x16x32_bf16 v[70:73], v[154:157], v[232:235], v[70:73]
	v_mfma_f32_16x16x32_bf16 v[70:73], v[158:161], v[236:239], v[70:73]
	v_mfma_f32_16x16x32_bf16 v[86:89], v[158:161], v[228:231], v[86:89]
	v_mfma_f32_16x16x32_bf16 v[86:89], v[154:157], v[206:209], v[86:89]
	v_mfma_f32_16x16x32_bf16 v[102:105], v[154:157], v[198:201], v[102:105]
	v_mfma_f32_16x16x32_bf16 v[102:105], v[158:161], v[202:205], v[102:105]
	v_mfma_f32_16x16x32_bf16 v[118:121], v[158:161], v[194:197], v[118:121]
	v_mfma_f32_16x16x32_bf16 v[118:121], v[154:157], v[190:193], v[118:121]
	v_mfma_f32_16x16x32_bf16 v[122:125], v[162:165], v[190:193], v[122:125]
	v_mfma_f32_16x16x32_bf16 v[122:125], v[166:169], v[194:197], v[122:125]
	v_mfma_f32_16x16x32_bf16 v[106:109], v[166:169], v[202:205], v[106:109]
	v_mfma_f32_16x16x32_bf16 v[106:109], v[162:165], v[198:201], v[106:109]
	v_mfma_f32_16x16x32_bf16 v[90:93], v[162:165], v[206:209], v[90:93]
	v_mfma_f32_16x16x32_bf16 v[90:93], v[166:169], v[228:231], v[90:93]
	v_mfma_f32_16x16x32_bf16 v[74:77], v[166:169], v[236:239], v[74:77]
	v_mfma_f32_16x16x32_bf16 v[74:77], v[162:165], v[232:235], v[74:77]
	v_mfma_f32_16x16x32_bf16 v[66:69], v[170:173], v[232:235], v[66:69]
	v_mfma_f32_16x16x32_bf16 v[66:69], v[178:181], v[236:239], v[66:69]
	v_mfma_f32_16x16x32_bf16 v[82:85], v[178:181], v[228:231], v[82:85]
	v_mfma_f32_16x16x32_bf16 v[82:85], v[170:173], v[206:209], v[82:85]
	v_mfma_f32_16x16x32_bf16 v[98:101], v[170:173], v[198:201], v[98:101]
	v_mfma_f32_16x16x32_bf16 v[98:101], v[178:181], v[202:205], v[98:101]
	v_mfma_f32_16x16x32_bf16 v[114:117], v[178:181], v[194:197], v[114:117]
	v_mfma_f32_16x16x32_bf16 v[114:117], v[170:173], v[190:193], v[114:117]
	s_barrier
	s_setprio 0
	s_add_i32 s22, s53, s26
	v_lshl_add_u64 v[140:141], v[140:141], 0, s[34:35]
	s_mov_b32 m0, s22
	ds_read_b128 v[190:193], v145 offset:49152
	ds_read_b128 v[194:197], v145 offset:50176
	ds_read_b128 v[198:201], v145 offset:51200
	ds_read_b128 v[202:205], v145 offset:52224
	ds_read_b128 v[206:209], v145 offset:53248
	ds_read_b128 v[228:231], v145 offset:54272
	ds_read_b128 v[232:235], v145 offset:55296
	ds_read_b128 v[236:239], v145 offset:56320
	global_load_lds_dwordx4 v[140:141], off
	s_add_i32 m0, s22, 0x2000
	s_add_u32 s18, s18, 0x100080
	v_lshl_add_u64 v[140:141], v[186:187], 0, s[34:35]
	s_addc_u32 s19, s19, 0
	s_add_i32 s22, s54, s26
	global_load_lds_dwordx4 v[140:141], off
	v_lshl_add_u64 v[140:141], s[18:19], 0, v[0:1]
	s_mov_b32 m0, s22
	s_nop 0
	global_load_lds_dwordx4 v[140:141], off
	v_lshl_add_u64 v[140:141], s[18:19], 0, v[130:131]
	s_add_i32 m0, s22, 0x2000
	s_nop 0
	global_load_lds_dwordx4 v[140:141], off
	v_lshl_add_u64 v[140:141], v[188:189], 0, s[34:35]
	s_mov_b32 m0, s43
	s_nop 0
	global_load_lds_dwordx4 v[140:141], off
	v_lshl_add_u64 v[140:141], v[210:211], 0, s[34:35]
	s_mov_b32 m0, s44
	s_nop 0
	global_load_lds_dwordx4 v[140:141], off
	s_waitcnt vmcnt(8)
	s_waitcnt lgkmcnt(0)
	s_setprio 1
	s_barrier
	v_mfma_f32_16x16x32_bf16 v[62:65], v[146:149], v[190:193], v[62:65]
	v_mfma_f32_16x16x32_bf16 v[62:65], v[150:153], v[194:197], v[62:65]
	v_mfma_f32_16x16x32_bf16 v[46:49], v[150:153], v[202:205], v[46:49]
	v_mfma_f32_16x16x32_bf16 v[46:49], v[146:149], v[198:201], v[46:49]
	v_mfma_f32_16x16x32_bf16 v[30:33], v[146:149], v[206:209], v[30:33]
	v_mfma_f32_16x16x32_bf16 v[30:33], v[150:153], v[228:231], v[30:33]
	v_mfma_f32_16x16x32_bf16 v[14:17], v[150:153], v[236:239], v[14:17]
	v_mfma_f32_16x16x32_bf16 v[14:17], v[146:149], v[232:235], v[14:17]
	v_mfma_f32_16x16x32_bf16 v[6:9], v[154:157], v[232:235], v[6:9]
	v_mfma_f32_16x16x32_bf16 v[6:9], v[158:161], v[236:239], v[6:9]
	v_mfma_f32_16x16x32_bf16 v[22:25], v[158:161], v[228:231], v[22:25]
	v_mfma_f32_16x16x32_bf16 v[22:25], v[154:157], v[206:209], v[22:25]
	v_mfma_f32_16x16x32_bf16 v[38:41], v[154:157], v[198:201], v[38:41]
	v_mfma_f32_16x16x32_bf16 v[38:41], v[158:161], v[202:205], v[38:41]
	v_mfma_f32_16x16x32_bf16 v[54:57], v[158:161], v[194:197], v[54:57]
	v_mfma_f32_16x16x32_bf16 v[54:57], v[154:157], v[190:193], v[54:57]
	v_mfma_f32_16x16x32_bf16 v[58:61], v[162:165], v[190:193], v[58:61]
	v_mfma_f32_16x16x32_bf16 v[58:61], v[166:169], v[194:197], v[58:61]
	v_mfma_f32_16x16x32_bf16 v[42:45], v[166:169], v[202:205], v[42:45]
	v_mfma_f32_16x16x32_bf16 v[42:45], v[162:165], v[198:201], v[42:45]
	v_mfma_f32_16x16x32_bf16 v[26:29], v[162:165], v[206:209], v[26:29]
	v_mfma_f32_16x16x32_bf16 v[26:29], v[166:169], v[228:231], v[26:29]
	v_mfma_f32_16x16x32_bf16 v[10:13], v[166:169], v[236:239], v[10:13]
	v_mfma_f32_16x16x32_bf16 v[10:13], v[162:165], v[232:235], v[10:13]
	v_mfma_f32_16x16x32_bf16 v[2:5], v[170:173], v[232:235], v[2:5]
	v_mfma_f32_16x16x32_bf16 v[2:5], v[178:181], v[236:239], v[2:5]
	v_mfma_f32_16x16x32_bf16 v[18:21], v[178:181], v[228:231], v[18:21]
	v_mfma_f32_16x16x32_bf16 v[18:21], v[170:173], v[206:209], v[18:21]
	v_mfma_f32_16x16x32_bf16 v[34:37], v[170:173], v[198:201], v[34:37]
	v_mfma_f32_16x16x32_bf16 v[34:37], v[178:181], v[202:205], v[34:37]
	v_mfma_f32_16x16x32_bf16 v[50:53], v[178:181], v[194:197], v[50:53]
	v_mfma_f32_16x16x32_bf16 v[50:53], v[170:173], v[190:193], v[50:53]
	s_barrier
	s_setprio 0
	s_add_i32 s52, s52, 2
	s_add_u32 s16, s16, 0x100
	s_addc_u32 s17, s17, 0
	s_add_u32 s50, s50, 0x100
	s_addc_u32 s51, s51, 0
	s_cmp_gt_u32 s52, 61
	s_cbranch_scc0 .LBB0_721
	s_and_b64 vcc, exec, s[2:3]
	s_cbranch_vccz .LBB0_724
	s_barrier

.LBB0_805:
	s_add_u32 s16, s14, 0x100
	s_addc_u32 s17, s15, 0
	s_add_i32 s49, 0, 0x10000
	s_cmpk_eq_i32 s48, 0xa8
	s_cselect_b32 s23, s5, s17
	s_cselect_b32 s22, s4, s16
	v_add_u32_e32 v140, s49, v143
	s_cselect_b32 s19, s9, s47
	s_cselect_b32 s18, s8, s46
	s_add_i32 s50, 0, 0x14000
	ds_read_b128 v[146:149], v140
	ds_read_b128 v[150:153], v140 offset:1024
	ds_read_b128 v[154:157], v140 offset:2048
	ds_read_b128 v[158:161], v140 offset:3072
	v_add_u32_e32 v140, s50, v143
	ds_read_b128 v[162:165], v140
	ds_read_b128 v[166:169], v140 offset:1024
	ds_read_b128 v[170:173], v140 offset:2048
	ds_read_b128 v[178:181], v140 offset:3072
	v_lshl_add_u64 v[140:141], s[14:15], 0, v[136:137]
	s_add_i32 m0, s31, 0xc000
	ds_read_b128 v[190:193], v145
	ds_read_b128 v[194:197], v145 offset:1024
	ds_read_b128 v[198:201], v145 offset:2048
	ds_read_b128 v[202:205], v145 offset:3072
	ds_read_b128 v[206:209], v145 offset:4096
	ds_read_b128 v[228:231], v145 offset:5120
	ds_read_b128 v[232:235], v145 offset:6144
	ds_read_b128 v[236:239], v145 offset:7168
	global_load_lds_dwordx4 v[140:141], off
	v_lshl_add_u64 v[140:141], s[14:15], 0, v[138:139]
	s_add_i32 m0, s31, 0xe000
	s_nop 0
	global_load_lds_dwordx4 v[140:141], off
	s_cmp_lg_u32 s48, 0xfffffffe
	s_cbranch_scc1 .Low_8_norm
	s_cmp_eq_u32 s41, 1
	s_cbranch_scc1 .Low_8_norm
	s_waitcnt vmcnt(24)
	s_branch .Low_8_done

.Low_8_done:
	s_waitcnt lgkmcnt(0)
	s_setprio 1
	s_barrier
	v_mfma_f32_16x16x32_bf16 v[126:129], v[146:149], v[190:193], v[126:129]
	v_mfma_f32_16x16x32_bf16 v[126:129], v[150:153], v[194:197], v[126:129]
	v_mfma_f32_16x16x32_bf16 v[118:121], v[150:153], v[202:205], v[118:121]
	v_mfma_f32_16x16x32_bf16 v[118:121], v[146:149], v[198:201], v[118:121]
	v_mfma_f32_16x16x32_bf16 v[102:105], v[146:149], v[206:209], v[102:105]
	v_mfma_f32_16x16x32_bf16 v[102:105], v[150:153], v[228:231], v[102:105]
	v_mfma_f32_16x16x32_bf16 v[86:89], v[150:153], v[236:239], v[86:89]
	v_mfma_f32_16x16x32_bf16 v[86:89], v[146:149], v[232:235], v[86:89]
	v_mfma_f32_16x16x32_bf16 v[78:81], v[154:157], v[232:235], v[78:81]
	v_mfma_f32_16x16x32_bf16 v[78:81], v[158:161], v[236:239], v[78:81]
	v_mfma_f32_16x16x32_bf16 v[94:97], v[158:161], v[228:231], v[94:97]
	v_mfma_f32_16x16x32_bf16 v[94:97], v[154:157], v[206:209], v[94:97]
	v_mfma_f32_16x16x32_bf16 v[110:113], v[154:157], v[198:201], v[110:113]
	v_mfma_f32_16x16x32_bf16 v[110:113], v[158:161], v[202:205], v[110:113]
	v_mfma_f32_16x16x32_bf16 v[122:125], v[158:161], v[194:197], v[122:125]
	v_mfma_f32_16x16x32_bf16 v[122:125], v[154:157], v[190:193], v[122:125]
	v_mfma_f32_16x16x32_bf16 v[114:117], v[162:165], v[190:193], v[114:117]
	v_mfma_f32_16x16x32_bf16 v[114:117], v[166:169], v[194:197], v[114:117]
	v_mfma_f32_16x16x32_bf16 v[98:101], v[166:169], v[202:205], v[98:101]
	v_mfma_f32_16x16x32_bf16 v[98:101], v[162:165], v[198:201], v[98:101]
	v_mfma_f32_16x16x32_bf16 v[82:85], v[162:165], v[206:209], v[82:85]
	v_mfma_f32_16x16x32_bf16 v[82:85], v[166:169], v[228:231], v[82:85]
	v_mfma_f32_16x16x32_bf16 v[70:73], v[166:169], v[236:239], v[70:73]
	v_mfma_f32_16x16x32_bf16 v[70:73], v[162:165], v[232:235], v[70:73]
	v_mfma_f32_16x16x32_bf16 v[66:69], v[170:173], v[232:235], v[66:69]
	v_mfma_f32_16x16x32_bf16 v[66:69], v[178:181], v[236:239], v[66:69]
	v_mfma_f32_16x16x32_bf16 v[74:77], v[178:181], v[228:231], v[74:77]
	v_mfma_f32_16x16x32_bf16 v[74:77], v[170:173], v[206:209], v[74:77]
	v_mfma_f32_16x16x32_bf16 v[90:93], v[170:173], v[198:201], v[90:93]
	v_mfma_f32_16x16x32_bf16 v[90:93], v[178:181], v[202:205], v[90:93]
	v_mfma_f32_16x16x32_bf16 v[106:109], v[178:181], v[194:197], v[106:109]
	v_mfma_f32_16x16x32_bf16 v[106:109], v[170:173], v[190:193], v[106:109]
	s_barrier
	s_setprio 0
	s_add_i32 s14, s49, s26
	v_lshl_add_u64 v[140:141], s[18:19], 0, v[0:1]
	s_mov_b32 m0, s14
	ds_read_b128 v[190:193], v145 offset:16384
	ds_read_b128 v[194:197], v145 offset:17408
	ds_read_b128 v[198:201], v145 offset:18432
	ds_read_b128 v[202:205], v145 offset:19456
	ds_read_b128 v[206:209], v145 offset:20480
	ds_read_b128 v[228:231], v145 offset:21504
	ds_read_b128 v[232:235], v145 offset:22528
	ds_read_b128 v[236:239], v145 offset:23552
	global_load_lds_dwordx4 v[140:141], off
	s_add_i32 m0, s14, 0x2000
	s_add_u32 s14, s18, 0x2b0000
	v_lshl_add_u64 v[186:187], s[18:19], 0, v[130:131]
	s_addc_u32 s15, s19, 0
	s_add_i32 s49, s50, s26
	global_load_lds_dwordx4 v[186:187], off
	v_lshl_add_u64 v[188:189], s[14:15], 0, v[0:1]
	s_mov_b32 m0, s49
	v_lshl_add_u64 v[210:211], s[22:23], 0, v[132:133]
	global_load_lds_dwordx4 v[188:189], off
	v_lshl_add_u64 v[188:189], s[14:15], 0, v[130:131]
	s_add_i32 m0, s49, 0x2000
	s_nop 0
	global_load_lds_dwordx4 v[188:189], off
	v_lshl_add_u64 v[188:189], s[22:23], 0, v[134:135]
	s_mov_b32 m0, s31
	s_nop 0
	global_load_lds_dwordx4 v[188:189], off
	s_mov_b32 m0, s36
	s_nop 0
	global_load_lds_dwordx4 v[210:211], off
	s_cmp_lg_u32 s48, 0xfffffffe
	s_cbranch_scc1 .Low_7_norm
	s_cmp_eq_u32 s41, 1
	s_cbranch_scc1 .Low_7_norm
	s_waitcnt vmcnt(24)
	s_branch .Low_7_done

.Low_7_done:
	s_waitcnt lgkmcnt(0)
	s_setprio 1
	s_barrier
	v_mfma_f32_16x16x32_bf16 v[62:65], v[146:149], v[190:193], v[62:65]
	v_mfma_f32_16x16x32_bf16 v[62:65], v[150:153], v[194:197], v[62:65]
	v_mfma_f32_16x16x32_bf16 v[54:57], v[150:153], v[202:205], v[54:57]
	v_mfma_f32_16x16x32_bf16 v[54:57], v[146:149], v[198:201], v[54:57]
	v_mfma_f32_16x16x32_bf16 v[38:41], v[146:149], v[206:209], v[38:41]
	v_mfma_f32_16x16x32_bf16 v[38:41], v[150:153], v[228:231], v[38:41]
	v_mfma_f32_16x16x32_bf16 v[22:25], v[150:153], v[236:239], v[22:25]
	v_mfma_f32_16x16x32_bf16 v[22:25], v[146:149], v[232:235], v[22:25]
	v_mfma_f32_16x16x32_bf16 v[14:17], v[154:157], v[232:235], v[14:17]
	v_mfma_f32_16x16x32_bf16 v[14:17], v[158:161], v[236:239], v[14:17]
	v_mfma_f32_16x16x32_bf16 v[30:33], v[158:161], v[228:231], v[30:33]
	v_mfma_f32_16x16x32_bf16 v[30:33], v[154:157], v[206:209], v[30:33]
	v_mfma_f32_16x16x32_bf16 v[46:49], v[154:157], v[198:201], v[46:49]
	v_mfma_f32_16x16x32_bf16 v[46:49], v[158:161], v[202:205], v[46:49]
	v_mfma_f32_16x16x32_bf16 v[58:61], v[158:161], v[194:197], v[58:61]
	v_mfma_f32_16x16x32_bf16 v[58:61], v[154:157], v[190:193], v[58:61]
	v_mfma_f32_16x16x32_bf16 v[50:53], v[162:165], v[190:193], v[50:53]
	v_mfma_f32_16x16x32_bf16 v[50:53], v[166:169], v[194:197], v[50:53]
	v_mfma_f32_16x16x32_bf16 v[34:37], v[166:169], v[202:205], v[34:37]
	v_mfma_f32_16x16x32_bf16 v[34:37], v[162:165], v[198:201], v[34:37]
	v_mfma_f32_16x16x32_bf16 v[18:21], v[162:165], v[206:209], v[18:21]
	v_mfma_f32_16x16x32_bf16 v[18:21], v[166:169], v[228:231], v[18:21]
	v_mfma_f32_16x16x32_bf16 v[6:9], v[166:169], v[236:239], v[6:9]
	v_mfma_f32_16x16x32_bf16 v[6:9], v[162:165], v[232:235], v[6:9]
	v_mfma_f32_16x16x32_bf16 v[2:5], v[170:173], v[232:235], v[2:5]
	v_mfma_f32_16x16x32_bf16 v[2:5], v[178:181], v[236:239], v[2:5]
	v_mfma_f32_16x16x32_bf16 v[10:13], v[178:181], v[228:231], v[10:13]
	v_mfma_f32_16x16x32_bf16 v[10:13], v[170:173], v[206:209], v[10:13]
	v_mfma_f32_16x16x32_bf16 v[26:29], v[170:173], v[198:201], v[26:29]
	v_mfma_f32_16x16x32_bf16 v[26:29], v[178:181], v[202:205], v[26:29]
	v_mfma_f32_16x16x32_bf16 v[42:45], v[178:181], v[194:197], v[42:45]
	v_mfma_f32_16x16x32_bf16 v[42:45], v[170:173], v[190:193], v[42:45]
	s_barrier
	s_setprio 0
	s_add_i32 s49, 0, 0x18000
	s_add_i32 s50, 0, 0x1c000
	v_add_u32_e32 v158, s49, v143
	v_add_u32_e32 v175, s50, v143
	ds_read_b128 v[146:149], v158
	ds_read_b128 v[150:153], v158 offset:1024
	ds_read_b128 v[154:157], v158 offset:2048
	ds_read_b128 v[158:161], v158 offset:3072
	ds_read_b128 v[162:165], v175
	ds_read_b128 v[166:169], v175 offset:1024
	ds_read_b128 v[170:173], v175 offset:2048
	ds_read_b128 v[178:181], v175 offset:3072
	s_add_u32 s14, s22, 0x2b0000
	s_addc_u32 s15, s23, 0
	s_mov_b32 m0, s37
	v_lshl_add_u64 v[226:227], s[14:15], 0, v[134:135]
	ds_read_b128 v[190:193], v145 offset:32768
	ds_read_b128 v[194:197], v145 offset:33792
	ds_read_b128 v[198:201], v145 offset:34816
	ds_read_b128 v[202:205], v145 offset:35840
	ds_read_b128 v[206:209], v145 offset:36864
	ds_read_b128 v[228:231], v145 offset:37888
	ds_read_b128 v[232:235], v145 offset:38912
	ds_read_b128 v[236:239], v145 offset:39936
	global_load_lds_dwordx4 v[226:227], off
	v_lshl_add_u64 v[226:227], s[14:15], 0, v[132:133]
	s_mov_b32 m0, s38
	s_nop 0
	global_load_lds_dwordx4 v[226:227], off
	s_waitcnt vmcnt(8)
	s_waitcnt lgkmcnt(0)
	s_setprio 1
	s_barrier
	v_mfma_f32_16x16x32_bf16 v[126:129], v[146:149], v[190:193], v[126:129]
	v_mfma_f32_16x16x32_bf16 v[126:129], v[150:153], v[194:197], v[126:129]
	v_mfma_f32_16x16x32_bf16 v[118:121], v[150:153], v[202:205], v[118:121]
	v_mfma_f32_16x16x32_bf16 v[118:121], v[146:149], v[198:201], v[118:121]
	v_mfma_f32_16x16x32_bf16 v[102:105], v[146:149], v[206:209], v[102:105]
	v_mfma_f32_16x16x32_bf16 v[102:105], v[150:153], v[228:231], v[102:105]
	v_mfma_f32_16x16x32_bf16 v[86:89], v[150:153], v[236:239], v[86:89]
	v_mfma_f32_16x16x32_bf16 v[86:89], v[146:149], v[232:235], v[86:89]
	v_mfma_f32_16x16x32_bf16 v[78:81], v[154:157], v[232:235], v[78:81]
	v_mfma_f32_16x16x32_bf16 v[78:81], v[158:161], v[236:239], v[78:81]
	v_mfma_f32_16x16x32_bf16 v[94:97], v[158:161], v[228:231], v[94:97]
	v_mfma_f32_16x16x32_bf16 v[94:97], v[154:157], v[206:209], v[94:97]
	v_mfma_f32_16x16x32_bf16 v[110:113], v[154:157], v[198:201], v[110:113]
	v_mfma_f32_16x16x32_bf16 v[110:113], v[158:161], v[202:205], v[110:113]
	v_mfma_f32_16x16x32_bf16 v[122:125], v[158:161], v[194:197], v[122:125]
	v_mfma_f32_16x16x32_bf16 v[122:125], v[154:157], v[190:193], v[122:125]
	v_mfma_f32_16x16x32_bf16 v[114:117], v[162:165], v[190:193], v[114:117]
	v_mfma_f32_16x16x32_bf16 v[114:117], v[166:169], v[194:197], v[114:117]
	v_mfma_f32_16x16x32_bf16 v[98:101], v[166:169], v[202:205], v[98:101]
	v_mfma_f32_16x16x32_bf16 v[98:101], v[162:165], v[198:201], v[98:101]
	v_mfma_f32_16x16x32_bf16 v[82:85], v[162:165], v[206:209], v[82:85]
	v_mfma_f32_16x16x32_bf16 v[82:85], v[166:169], v[228:231], v[82:85]
	v_mfma_f32_16x16x32_bf16 v[70:73], v[166:169], v[236:239], v[70:73]
	v_mfma_f32_16x16x32_bf16 v[70:73], v[162:165], v[232:235], v[70:73]
	v_mfma_f32_16x16x32_bf16 v[66:69], v[170:173], v[232:235], v[66:69]
	v_mfma_f32_16x16x32_bf16 v[66:69], v[178:181], v[236:239], v[66:69]
	v_mfma_f32_16x16x32_bf16 v[74:77], v[178:181], v[228:231], v[74:77]
	v_mfma_f32_16x16x32_bf16 v[74:77], v[170:173], v[206:209], v[74:77]
	v_mfma_f32_16x16x32_bf16 v[90:93], v[170:173], v[198:201], v[90:93]
	v_mfma_f32_16x16x32_bf16 v[90:93], v[178:181], v[202:205], v[90:93]
	v_mfma_f32_16x16x32_bf16 v[106:109], v[178:181], v[194:197], v[106:109]
	v_mfma_f32_16x16x32_bf16 v[106:109], v[170:173], v[190:193], v[106:109]
	s_barrier
	s_setprio 0
	s_add_i32 s14, s49, s26
	v_lshl_add_u64 v[140:141], v[140:141], 0, s[34:35]
	s_mov_b32 m0, s14
	ds_read_b128 v[190:193], v145 offset:49152
	ds_read_b128 v[194:197], v145 offset:50176
	ds_read_b128 v[198:201], v145 offset:51200
	ds_read_b128 v[202:205], v145 offset:52224
	ds_read_b128 v[206:209], v145 offset:53248
	ds_read_b128 v[228:231], v145 offset:54272
	ds_read_b128 v[232:235], v145 offset:55296
	ds_read_b128 v[236:239], v145 offset:56320
	global_load_lds_dwordx4 v[140:141], off
	s_add_i32 m0, s14, 0x2000
	s_add_u32 s14, s18, 0x2b0080
	v_lshl_add_u64 v[140:141], v[186:187], 0, s[34:35]
	s_addc_u32 s15, s19, 0
	s_add_i32 s18, s50, s26
	global_load_lds_dwordx4 v[140:141], off
	v_lshl_add_u64 v[140:141], s[14:15], 0, v[0:1]
	s_mov_b32 m0, s18
	s_nop 0
	global_load_lds_dwordx4 v[140:141], off
	v_lshl_add_u64 v[140:141], s[14:15], 0, v[130:131]
	s_add_i32 m0, s18, 0x2000
	s_nop 0
	global_load_lds_dwordx4 v[140:141], off
	v_lshl_add_u64 v[140:141], v[188:189], 0, s[34:35]
	s_mov_b32 m0, s39
	s_nop 0
	global_load_lds_dwordx4 v[140:141], off
	v_lshl_add_u64 v[140:141], v[210:211], 0, s[34:35]
	s_mov_b32 m0, s40
	s_nop 0
	global_load_lds_dwordx4 v[140:141], off
	s_waitcnt vmcnt(8)
	s_waitcnt lgkmcnt(0)
	s_setprio 1
	s_barrier
	v_mfma_f32_16x16x32_bf16 v[62:65], v[146:149], v[190:193], v[62:65]
	v_mfma_f32_16x16x32_bf16 v[62:65], v[150:153], v[194:197], v[62:65]
	v_mfma_f32_16x16x32_bf16 v[54:57], v[150:153], v[202:205], v[54:57]
	v_mfma_f32_16x16x32_bf16 v[54:57], v[146:149], v[198:201], v[54:57]
	v_mfma_f32_16x16x32_bf16 v[38:41], v[146:149], v[206:209], v[38:41]
	v_mfma_f32_16x16x32_bf16 v[38:41], v[150:153], v[228:231], v[38:41]
	v_mfma_f32_16x16x32_bf16 v[22:25], v[150:153], v[236:239], v[22:25]
	v_mfma_f32_16x16x32_bf16 v[22:25], v[146:149], v[232:235], v[22:25]
	v_mfma_f32_16x16x32_bf16 v[14:17], v[154:157], v[232:235], v[14:17]
	v_mfma_f32_16x16x32_bf16 v[14:17], v[158:161], v[236:239], v[14:17]
	v_mfma_f32_16x16x32_bf16 v[30:33], v[158:161], v[228:231], v[30:33]
	v_mfma_f32_16x16x32_bf16 v[30:33], v[154:157], v[206:209], v[30:33]
	v_mfma_f32_16x16x32_bf16 v[46:49], v[154:157], v[198:201], v[46:49]
	v_mfma_f32_16x16x32_bf16 v[46:49], v[158:161], v[202:205], v[46:49]
	v_mfma_f32_16x16x32_bf16 v[58:61], v[158:161], v[194:197], v[58:61]
	v_mfma_f32_16x16x32_bf16 v[58:61], v[154:157], v[190:193], v[58:61]
	v_mfma_f32_16x16x32_bf16 v[50:53], v[162:165], v[190:193], v[50:53]
	v_mfma_f32_16x16x32_bf16 v[50:53], v[166:169], v[194:197], v[50:53]
	v_mfma_f32_16x16x32_bf16 v[34:37], v[166:169], v[202:205], v[34:37]
	v_mfma_f32_16x16x32_bf16 v[34:37], v[162:165], v[198:201], v[34:37]
	v_mfma_f32_16x16x32_bf16 v[18:21], v[162:165], v[206:209], v[18:21]
	v_mfma_f32_16x16x32_bf16 v[18:21], v[166:169], v[228:231], v[18:21]
	v_mfma_f32_16x16x32_bf16 v[6:9], v[166:169], v[236:239], v[6:9]
	v_mfma_f32_16x16x32_bf16 v[6:9], v[162:165], v[232:235], v[6:9]
	v_mfma_f32_16x16x32_bf16 v[2:5], v[170:173], v[232:235], v[2:5]
	v_mfma_f32_16x16x32_bf16 v[2:5], v[178:181], v[236:239], v[2:5]
	v_mfma_f32_16x16x32_bf16 v[10:13], v[178:181], v[228:231], v[10:13]
	v_mfma_f32_16x16x32_bf16 v[10:13], v[170:173], v[206:209], v[10:13]
	v_mfma_f32_16x16x32_bf16 v[26:29], v[170:173], v[198:201], v[26:29]
	v_mfma_f32_16x16x32_bf16 v[26:29], v[178:181], v[202:205], v[26:29]
	v_mfma_f32_16x16x32_bf16 v[42:45], v[178:181], v[194:197], v[42:45]
	v_mfma_f32_16x16x32_bf16 v[42:45], v[170:173], v[190:193], v[42:45]
	s_barrier
	s_setprio 0
	s_add_i32 s48, s48, 2
	s_add_u32 s46, s46, 0x100
	s_addc_u32 s47, s47, 0
	s_cmpk_gt_u32 s48, 0xa9
	s_mov_b64 s[14:15], s[16:17]
	s_cbranch_scc0 .LBB0_805
	s_and_b64 vcc, exec, s[6:7]
	s_cbranch_vccz .LBB0_808
	s_barrier
